# sample split-K partial slabs stored write-through (sc1) so the final grid barrier's L2 writeback is short; on top of v78
# baseline (speedup 1.0000x reference)
;     __device__ __forceinline__ void operator()(f32x4 (&acc)[2][2][4][2], const Unit& u, int wr, int wc, int fr, int fq, LAS unsigned char* lds) const {
;     ...
;         const int row0 = u.pm * BM + wr * 64 + fr - MP; const int col0 = u.pn * BM + wc * 32 + 8 * fq;
; #pragma unroll
;         for (int ai = 0; ai < 2; ++ai)
; #pragma unroll
;             for (int m = 0; m < 4; ++m) { float* orow = part + ((size_t)u.ks * MS + row0 + ai * HALF + m * 16) * DM + col0;
; #pragma unroll
;                 for (int bj = 0; bj < 2; ++bj) { *(f32x4*)(orow + bj * HALF) = acc[ai][bj][m][0]; *(f32x4*)(orow + bj * HALF + 4) = acc[ai][bj][m][1]; } }
.LBB0_1259:
	s_lshl_b32 s4, s20, 8
	v_mov_b32_e32 v129, v180
	s_add_i32 s4, s4, s43
	s_addk_i32 s4, 0x8000
	v_and_or_b32 v128, v129, 15, s4
	s_lshl_b32 s1, s1, 8
	v_lshrrev_b32_e32 v129, 1, v129
	v_and_or_b32 v129, v129, 24, s1
	s_ashr_i32 s1, s0, 31
	s_lshl_b64 s[0:1], s[0:1], 22
	s_add_u32 s0, s28, s0
	s_addc_u32 s1, s29, s1
	v_or_b32_e32 v132, s44, v129
	v_ashrrev_i32_e32 v129, 31, v128
	s_add_u32 s0, s0, 0x1e900000
	v_lshlrev_b64 v[128:129], 12, v[128:129]
	s_addc_u32 s1, s1, 0
	v_lshl_add_u64 v[130:131], s[0:1], 0, v[128:129]
	v_lshlrev_b32_e32 v132, 2, v132
	v_mov_b32_e32 v133, 0
	v_lshl_add_u64 v[130:131], v[130:131], 0, v[132:133]
	global_store_dwordx4 v[130:131], v[124:127], off sc1
	global_store_dwordx4 v[130:131], v[120:123], off offset:16 sc1
	global_store_dwordx4 v[130:131], v[104:107], off offset:512 sc1
	global_store_dwordx4 v[130:131], v[96:99], off offset:528 sc1
	s_nop 1
	v_or_b32_e32 v96, 0x10000, v128
	v_mov_b32_e32 v97, v129
	v_lshl_add_u64 v[96:97], s[0:1], 0, v[96:97]
	v_lshl_add_u64 v[96:97], v[96:97], 0, v[132:133]
	global_store_dwordx4 v[96:97], v[116:119], off sc1
	global_store_dwordx4 v[96:97], v[112:115], off offset:16 sc1
	global_store_dwordx4 v[96:97], v[88:91], off offset:512 sc1
	global_store_dwordx4 v[96:97], v[80:83], off offset:528 sc1
	s_nop 1
	v_or_b32_e32 v80, 0x20000, v128
	v_mov_b32_e32 v81, v129
	v_lshl_add_u64 v[80:81], s[0:1], 0, v[80:81]
	v_lshl_add_u64 v[80:81], v[80:81], 0, v[132:133]
	v_or_b32_e32 v128, 0x30000, v128
	global_store_dwordx4 v[80:81], v[108:111], off sc1
	global_store_dwordx4 v[80:81], v[100:103], off offset:16 sc1
	global_store_dwordx4 v[80:81], v[76:79], off offset:512 sc1
	global_store_dwordx4 v[80:81], v[72:75], off offset:528 sc1
	s_nop 1
	v_lshl_add_u64 v[72:73], s[0:1], 0, v[128:129]
	v_lshl_add_u64 v[72:73], v[72:73], 0, v[132:133]
	s_mov_b64 s[0:1], 0x80000
	global_store_dwordx4 v[72:73], v[92:95], off sc1
	global_store_dwordx4 v[72:73], v[84:87], off offset:16 sc1
	global_store_dwordx4 v[72:73], v[68:71], off offset:512 sc1
	global_store_dwordx4 v[72:73], v[64:67], off offset:528 sc1
	s_nop 1
	v_lshl_add_u64 v[64:65], v[130:131], 0, s[0:1]
	s_mov_b32 s0, 0x80000
	v_add_co_u32_e32 v66, vcc, s0, v130
	s_mov_b64 s[0:1], 0x90000
	s_nop 0
	v_addc_co_u32_e32 v67, vcc, 0, v131, vcc
	global_store_dwordx4 v[66:67], v[60:63], off sc1
	global_store_dwordx4 v[64:65], v[56:59], off offset:16 sc1
	global_store_dwordx4 v[64:65], v[44:47], off offset:512 sc1
	global_store_dwordx4 v[64:65], v[36:39], off offset:528 sc1
	s_nop 1
	v_lshl_add_u64 v[36:37], v[130:131], 0, s[0:1]
	s_mov_b32 s0, 0x90000
	v_add_co_u32_e32 v38, vcc, s0, v130
	s_mov_b64 s[0:1], 0xa0000
	s_nop 0
	v_addc_co_u32_e32 v39, vcc, 0, v131, vcc
	global_store_dwordx4 v[38:39], v[52:55], off sc1
	global_store_dwordx4 v[36:37], v[48:51], off offset:16 sc1
	global_store_dwordx4 v[36:37], v[28:31], off offset:512 sc1
	global_store_dwordx4 v[36:37], v[20:23], off offset:528 sc1
	s_nop 1
	v_lshl_add_u64 v[20:21], v[130:131], 0, s[0:1]
	s_mov_b32 s0, 0xa0000
	v_add_co_u32_e32 v22, vcc, s0, v130
	s_mov_b64 s[0:1], 0xb0000
	s_nop 0
	v_addc_co_u32_e32 v23, vcc, 0, v131, vcc
	global_store_dwordx4 v[22:23], v[40:43], off sc1
	global_store_dwordx4 v[20:21], v[32:35], off offset:16 sc1
	global_store_dwordx4 v[20:21], v[12:15], off offset:512 sc1
	global_store_dwordx4 v[20:21], v[8:11], off offset:528 sc1
	s_nop 1
	v_add_co_u32_e32 v10, vcc, 0xb0000, v130
	v_lshl_add_u64 v[8:9], v[130:131], 0, s[0:1]
	s_nop 0
	v_addc_co_u32_e32 v11, vcc, 0, v131, vcc
	global_store_dwordx4 v[10:11], v[24:27], off sc1
	global_store_dwordx4 v[8:9], v[16:19], off offset:16 sc1
	global_store_dwordx4 v[8:9], v[4:7], off offset:512 sc1
	global_store_dwordx4 v[8:9], v[0:3], off offset:528 sc1
	s_waitcnt vmcnt(0)
	s_barrier
